# second per-layer wait on the weight-conversion counter removed (same counter and threshold were already waited on before the gate/up GEMM)
# speedup vs baseline: 1.0144x; 1.0033x over previous
; #define CONV_WAIT(n) do { ArgsP A_ = get_args(); if (tid_now(wave_s) == 0) { unsigned sp_ = 0u; while (xb_ld(CONV_WORD(n)) < (unsigned)(G / 2)) { __builtin_amdgcn_s_sleep(1); if (++sp_ > XB_SPIN_CAP) break; } \
;         __builtin_amdgcn_fence(__ATOMIC_ACQUIRE, "agent"); asm volatile("s_waitcnt vmcnt(0)" ::: "memory"); } __syncthreads(); } while (0)
; __global__ void __launch_bounds__(NWAVES * 64, 2) fwd_megakernel(Args args_unused) {
;     ...
;         if (i > 0) CONV_WAIT(i);
.LBB0_771:
	s_andn2_b64 vcc, exec, s[4:5]
	s_branch .LBB0_783
	s_mov_b64 s[0:1], s[78:79]
	v_mbcnt_lo_u32_b32 v0, -1, 0
	v_mbcnt_hi_u32_b32 v0, -1, v0
	s_nop 0
	v_cmp_eq_u32_e32 vcc, s81, v0
	s_and_saveexec_b64 s[4:5], vcc
	s_cbranch_execz .LBB0_782
	s_load_dwordx2 s[0:1], s[0:1], 0xa0
	s_lshl_b32 s50, s20, 6
	s_lshl_b64 s[6:7], s[50:51], 2
	s_mov_b32 s8, 0x400001
	s_waitcnt lgkmcnt(0)
	s_add_u32 s0, s0, s6
	s_addc_u32 s1, s1, s7
	s_add_u32 s6, s0, 0x26134000
	s_addc_u32 s7, s1, 0
	s_branch .LBB0_775
